# P3 prologue: wave 0 issues q/k-norm gain loads before the bias-table load (one round trip); plus earlier edits
# speedup vs baseline: 1.0061x; 1.0023x over previous
; __global__ void __launch_bounds__(NWAVES * 64, 2) fwd(Args a) {
;     ...
;             __syncthreads();
;             { const int dr = tid >> 5, dc = tid & 31; tbl[tid] = (dr < 15 && dc < 31) ? a.in[I_RPB][h * 465 + dr * 31 + dc] * 1.4426950408889634f : -1e30f; }
;             if (tid < 64) qgt[tid] = a.in[I_QNG][tid] * a.in[I_KNG][tid];
.LBB0_234:
	v_mov_b32_e32 v2, 0xf149f2ca
	s_barrier
	s_and_saveexec_b64 s[98:99], s[0:1]
	s_cbranch_execz .Lqg_skip
	global_load_dword v240, v[130:131], off
	global_load_dword v241, v[128:129], off
.Lqg_skip:
	s_or_b64 exec, exec, s[98:99]
	s_and_saveexec_b64 s[12:13], s[48:49]
	s_cbranch_execz .LBB0_236
	s_mul_i32 s28, s52, 0x1d1
	v_add_u32_e32 v4, s28, v126
	v_readlane_b32 s68, v250, 20
	v_ashrrev_i32_e32 v5, 31, v4
	v_readlane_b32 s74, v250, 26
	v_readlane_b32 s75, v250, 27
	v_readlane_b32 s69, v250, 21
	v_readlane_b32 s70, v250, 22
	v_lshl_add_u64 v[4:5], v[4:5], 2, s[74:75]
	global_load_dword v2, v[4:5], off
	v_readlane_b32 s71, v250, 23
	v_readlane_b32 s72, v250, 24
	v_readlane_b32 s73, v250, 25
	v_readlane_b32 s76, v250, 28
	v_readlane_b32 s77, v250, 29
	v_readlane_b32 s78, v250, 30
	v_readlane_b32 s79, v250, 31
	v_readlane_b32 s80, v250, 32
	v_readlane_b32 s81, v250, 33
	v_readlane_b32 s82, v250, 34
	v_readlane_b32 s83, v250, 35
	s_waitcnt vmcnt(0)
	v_mul_f32_e32 v2, 0x3fb8aa3b, v2
.LBB0_236:
	s_or_b64 exec, exec, s[12:13]
	ds_write_b32 v127, v2
	s_and_saveexec_b64 s[12:13], s[0:1]
	s_cbranch_execz .LBB0_238
	s_waitcnt vmcnt(0)
	v_mul_f32_e32 v2, v240, v241
	ds_write_b32 v168, v2
